# in-proj epilogue q/k/v path: row groups 1-7 take their two store addresses from group 0 plus a scalar row delta (98 fewer VALU per unit)
# baseline (speedup 1.0000x reference)
; __device__ __forceinline__ unsigned pk2(float lo, float hi) { f32x2_t v = {lo, hi}; bf16x2_t b = __builtin_convertvector(v, bf16x2_t); return __builtin_bit_cast(unsigned, b); }
; __device__ __forceinline__ float silu_f(float v) { return v * __builtin_amdgcn_rcpf(1.f + __builtin_amdgcn_exp2f(-v * LOG2E)); }
; template <int CTRL> __device__ __forceinline__ unsigned dpp_mov(unsigned v) { return (unsigned)__builtin_amdgcn_update_dpp(0, (int)v, CTRL, 0xF, 0xF, true); }
;     __device__ __forceinline__ void operator()(const pg8::f32x4 (&acc)[2][2][4][2], const pg8::Unit& u, int wr, int wc, int fr, int fq) const {
;     ...
;                 pg8::f32x4 a0 = acc[ai][0][m][0], a1 = acc[ai][0][m][1], b0 = acc[ai][1][m][0], b1 = acc[ai][1][m][1];
;                 if (act) {
; #pragma unroll
;                     for (int e = 0; e < 4; ++e) { a0[e] = silu_f(a0[e]); a1[e] = silu_f(a1[e]); b0[e] = silu_f(b0[e]); b1[e] = silu_f(b1[e]); } }
;                 u32x4 A, B; A.x = pk2(a0[0], a0[1]); A.y = pk2(a0[2], a0[3]); A.z = pk2(a1[0], a1[1]); A.w = pk2(a1[2], a1[3]);
;                 B.x = pk2(b0[0], b0[1]); B.y = pk2(b0[2], b0[3]); B.z = pk2(b1[0], b1[1]); B.w = pk2(b1[2], b1[3]);
;                 u32x4 snd, rcv;
; #pragma unroll
;                 for (int e = 0; e < 4; ++e) { snd[e] = hi8 ? A[e] : B[e]; rcv[e] = dpp_mov<0x128>(snd[e]); }
;                 u32x4 d1, d2;
; #pragma unroll
;                 for (int e = 0; e < 4; ++e) { d1[e] = hi8 ? rcv[e] : A[e]; d2[e] = hi8 ? B[e] : rcv[e]; }
;                 const int row1 = rbase + ai * 128 + m * 16, row2 = row1 + 8;
;                 if (qkv) {
;                     const int bb = row1 >> 13, t1 = row1 & (SEQ - 1), t2 = row2 & (SEQ - 1);
;                     const int p1 = (t1 & dmask) * Lc + (t1 >> dsh), p2 = (t2 & dmask) * Lc + (t2 >> dsh);
;                     bf16_t* hb = base + (size_t)bb * 24 * SEQ * 64 + ecol;
;                     *(u32x4*)(hb + (size_t)p1 * 64) = d1; *(u32x4*)(hb + (size_t)p2 * 64) = d2;
.Lp1_nn0:
	s_lshl_b32 s6, s6, 8
	s_add_i32 s62, s6, s74
	s_lshl_b64 s[6:7], s[8:9], 1
	s_add_u32 s6, s60, s6
	s_addc_u32 s7, s61, s7
	s_sub_i32 s21, 13, s17
	v_lshl_add_u64 v[140:141], s[6:7], 0, v[132:133]
	s_and_b64 s[6:7], s[58:59], exec
	s_cselect_b32 s8, 9, 10
	s_ashr_i32 s6, s62, 13
	v_cvt_pk_bf16_f32 v124, v124, v125
	v_cvt_pk_bf16_f32 v125, v126, v127
	v_cvt_pk_bf16_f32 v120, v120, v121
	v_cvt_pk_bf16_f32 v121, v122, v123
	v_cvt_pk_bf16_f32 v117, v116, v117
	v_cvt_pk_bf16_f32 v118, v118, v119
	v_cvt_pk_bf16_f32 v119, v112, v113
	v_cvt_pk_bf16_f32 v115, v114, v115
	s_mul_i32 s6, s6, 24
	v_cndmask_b32_e64 v112, v124, v117, s[0:1]
	v_cndmask_b32_e64 v113, v125, v118, s[0:1]
	v_cndmask_b32_e64 v114, v120, v119, s[0:1]
	v_cndmask_b32_e64 v116, v121, v115, s[0:1]
	s_ashr_i32 s7, s6, 31
	v_mov_b32_dpp v112, v112 row_ror:8 row_mask:0xf bank_mask:0xf bound_ctrl:1
	v_mov_b32_dpp v113, v113 row_ror:8 row_mask:0xf bank_mask:0xf bound_ctrl:1
	v_mov_b32_dpp v114, v114 row_ror:8 row_mask:0xf bank_mask:0xf bound_ctrl:1
	v_mov_b32_dpp v122, v116 row_ror:8 row_mask:0xf bank_mask:0xf bound_ctrl:1
	s_lshl_b64 s[6:7], s[6:7], 20
	v_or_b32_e32 v142, s62, v147
	v_cndmask_b32_e64 v116, v112, v124, s[0:1]
	v_cndmask_b32_e64 v112, v117, v112, s[0:1]
	v_cndmask_b32_e64 v117, v113, v125, s[0:1]
	v_cndmask_b32_e64 v113, v118, v113, s[0:1]
	v_cndmask_b32_e64 v118, v114, v120, s[0:1]
	v_cndmask_b32_e64 v114, v119, v114, s[0:1]
	v_cndmask_b32_e64 v119, v122, v121, s[0:1]
	v_cndmask_b32_e64 v121, 0, 1, s[28:29]
	v_lshl_add_u64 v[144:145], v[140:141], 0, s[6:7]
	v_cndmask_b32_e64 v115, v115, v122, s[0:1]
	v_or_b32_e32 v120, 8, v142
	v_cmp_ne_u32_e64 s[6:7], 1, v121
	s_andn2_b64 vcc, exec, s[28:29]
	s_mov_b64 s[28:29], -1
	s_cbranch_vccnz .LBB0_206
	v_and_b32_e32 v121, 0x1fc7, v142
	v_lshlrev_b32_e32 v123, s21, v142
	v_and_b32_e32 v122, 0x1fcf, v120
	v_and_b32_e32 v123, 0x1ffe, v123
	v_lshrrev_b32_e32 v121, s17, v121
	v_lshlrev_b32_e32 v124, s21, v120
	v_lshrrev_b32_e32 v125, s17, v122
	v_add_lshl_u32 v122, v123, v121, 7
	v_mov_b32_e32 v123, v133
	v_and_b32_e32 v124, 0x1ffe, v124
	v_lshl_add_u64 v[252:253], v[144:145], 0, v[122:123]
	global_store_dwordx4 v[252:253], v[116:119], off
	v_add_lshl_u32 v122, v124, v125, 7
	v_mov_b32_e32 v123, v133
	v_lshl_add_u64 v[254:255], v[144:145], 0, v[122:123]
	global_store_dwordx4 v[254:255], v[112:115], off
	s_cbranch_execz .LBB0_207

; __device__ __forceinline__ unsigned pk2(float lo, float hi) { f32x2_t v = {lo, hi}; bf16x2_t b = __builtin_convertvector(v, bf16x2_t); return __builtin_bit_cast(unsigned, b); }
; __device__ __forceinline__ float silu_f(float v) { return v * __builtin_amdgcn_rcpf(1.f + __builtin_amdgcn_exp2f(-v * LOG2E)); }
; template <int CTRL> __device__ __forceinline__ unsigned dpp_mov(unsigned v) { return (unsigned)__builtin_amdgcn_update_dpp(0, (int)v, CTRL, 0xF, 0xF, true); }
;     __device__ __forceinline__ void operator()(const pg8::f32x4 (&acc)[2][2][4][2], const pg8::Unit& u, int wr, int wc, int fr, int fq) const {
;     ...
;                 pg8::f32x4 a0 = acc[ai][0][m][0], a1 = acc[ai][0][m][1], b0 = acc[ai][1][m][0], b1 = acc[ai][1][m][1];
;                 if (act) {
; #pragma unroll
;                     for (int e = 0; e < 4; ++e) { a0[e] = silu_f(a0[e]); a1[e] = silu_f(a1[e]); b0[e] = silu_f(b0[e]); b1[e] = silu_f(b1[e]); } }
;                 u32x4 A, B; A.x = pk2(a0[0], a0[1]); A.y = pk2(a0[2], a0[3]); A.z = pk2(a1[0], a1[1]); A.w = pk2(a1[2], a1[3]);
;                 B.x = pk2(b0[0], b0[1]); B.y = pk2(b0[2], b0[3]); B.z = pk2(b1[0], b1[1]); B.w = pk2(b1[2], b1[3]);
;                 u32x4 snd, rcv;
; #pragma unroll
;                 for (int e = 0; e < 4; ++e) { snd[e] = hi8 ? A[e] : B[e]; rcv[e] = dpp_mov<0x128>(snd[e]); }
;                 u32x4 d1, d2;
; #pragma unroll
;                 for (int e = 0; e < 4; ++e) { d1[e] = hi8 ? rcv[e] : A[e]; d2[e] = hi8 ? B[e] : rcv[e]; }
;                 const int row1 = rbase + ai * 128 + m * 16, row2 = row1 + 8;
;                 if (qkv) {
;                     const int bb = row1 >> 13, t1 = row1 & (SEQ - 1), t2 = row2 & (SEQ - 1);
;                     const int p1 = (t1 & dmask) * Lc + (t1 >> dsh), p2 = (t2 & dmask) * Lc + (t2 >> dsh);
;                     bf16_t* hb = base + (size_t)bb * 24 * SEQ * 64 + ecol;
;                     *(u32x4*)(hb + (size_t)p1 * 64) = d1; *(u32x4*)(hb + (size_t)p2 * 64) = d2;
.Lp1_nn1:
	v_cvt_pk_bf16_f32 v108, v108, v109
	v_cvt_pk_bf16_f32 v109, v110, v111
	v_cvt_pk_bf16_f32 v104, v104, v105
	v_cvt_pk_bf16_f32 v105, v106, v107
	v_cvt_pk_bf16_f32 v101, v100, v101
	v_cvt_pk_bf16_f32 v102, v102, v103
	v_cvt_pk_bf16_f32 v103, v96, v97
	v_cvt_pk_bf16_f32 v99, v98, v99
	v_cndmask_b32_e64 v96, v108, v101, s[0:1]
	v_cndmask_b32_e64 v97, v109, v102, s[0:1]
	v_cndmask_b32_e64 v98, v104, v103, s[0:1]
	v_cndmask_b32_e64 v100, v105, v99, s[0:1]
	v_mov_b32_dpp v96, v96 row_ror:8 row_mask:0xf bank_mask:0xf bound_ctrl:1
	v_mov_b32_dpp v97, v97 row_ror:8 row_mask:0xf bank_mask:0xf bound_ctrl:1
	v_mov_b32_dpp v98, v98 row_ror:8 row_mask:0xf bank_mask:0xf bound_ctrl:1
	v_mov_b32_dpp v106, v100 row_ror:8 row_mask:0xf bank_mask:0xf bound_ctrl:1
	v_cndmask_b32_e64 v100, v96, v108, s[0:1]
	v_cndmask_b32_e64 v96, v101, v96, s[0:1]
	v_cndmask_b32_e64 v101, v97, v109, s[0:1]
	v_cndmask_b32_e64 v97, v102, v97, s[0:1]
	v_cndmask_b32_e64 v102, v98, v104, s[0:1]
	v_cndmask_b32_e64 v98, v103, v98, s[0:1]
	v_cndmask_b32_e64 v103, v106, v105, s[0:1]
	v_cndmask_b32_e64 v99, v99, v106, s[0:1]
	v_or_b32_e32 v106, 16, v142
	v_or_b32_e32 v104, 24, v142
	s_and_b64 vcc, exec, s[6:7]
	s_mov_b64 s[28:29], -1
	s_cbranch_vccnz .LBB0_208
	s_lshr_b32 vcc_lo, 0x800, s17
	s_mov_b32 vcc_hi, 0
	v_lshl_add_u64 v[108:109], v[252:253], 0, vcc
	global_store_dwordx4 v[108:109], v[100:103], off
	v_lshl_add_u64 v[108:109], v[254:255], 0, vcc
	global_store_dwordx4 v[108:109], v[96:99], off
	s_cbranch_execz .LBB0_209

; __device__ __forceinline__ unsigned pk2(float lo, float hi) { f32x2_t v = {lo, hi}; bf16x2_t b = __builtin_convertvector(v, bf16x2_t); return __builtin_bit_cast(unsigned, b); }
; __device__ __forceinline__ float silu_f(float v) { return v * __builtin_amdgcn_rcpf(1.f + __builtin_amdgcn_exp2f(-v * LOG2E)); }
; template <int CTRL> __device__ __forceinline__ unsigned dpp_mov(unsigned v) { return (unsigned)__builtin_amdgcn_update_dpp(0, (int)v, CTRL, 0xF, 0xF, true); }
;     __device__ __forceinline__ void operator()(const pg8::f32x4 (&acc)[2][2][4][2], const pg8::Unit& u, int wr, int wc, int fr, int fq) const {
;     ...
;                 pg8::f32x4 a0 = acc[ai][0][m][0], a1 = acc[ai][0][m][1], b0 = acc[ai][1][m][0], b1 = acc[ai][1][m][1];
;                 if (act) {
; #pragma unroll
;                     for (int e = 0; e < 4; ++e) { a0[e] = silu_f(a0[e]); a1[e] = silu_f(a1[e]); b0[e] = silu_f(b0[e]); b1[e] = silu_f(b1[e]); } }
;                 u32x4 A, B; A.x = pk2(a0[0], a0[1]); A.y = pk2(a0[2], a0[3]); A.z = pk2(a1[0], a1[1]); A.w = pk2(a1[2], a1[3]);
;                 B.x = pk2(b0[0], b0[1]); B.y = pk2(b0[2], b0[3]); B.z = pk2(b1[0], b1[1]); B.w = pk2(b1[2], b1[3]);
;                 u32x4 snd, rcv;
; #pragma unroll
;                 for (int e = 0; e < 4; ++e) { snd[e] = hi8 ? A[e] : B[e]; rcv[e] = dpp_mov<0x128>(snd[e]); }
;                 u32x4 d1, d2;
; #pragma unroll
;                 for (int e = 0; e < 4; ++e) { d1[e] = hi8 ? rcv[e] : A[e]; d2[e] = hi8 ? B[e] : rcv[e]; }
;                 const int row1 = rbase + ai * 128 + m * 16, row2 = row1 + 8;
;                 if (qkv) {
;                     const int bb = row1 >> 13, t1 = row1 & (SEQ - 1), t2 = row2 & (SEQ - 1);
;                     const int p1 = (t1 & dmask) * Lc + (t1 >> dsh), p2 = (t2 & dmask) * Lc + (t2 >> dsh);
;                     bf16_t* hb = base + (size_t)bb * 24 * SEQ * 64 + ecol;
;                     *(u32x4*)(hb + (size_t)p1 * 64) = d1; *(u32x4*)(hb + (size_t)p2 * 64) = d2;
.Lp1_nn2:
	v_cvt_pk_bf16_f32 v92, v92, v93
	v_cvt_pk_bf16_f32 v93, v94, v95
	v_cvt_pk_bf16_f32 v88, v88, v89
	v_cvt_pk_bf16_f32 v89, v90, v91
	v_cvt_pk_bf16_f32 v85, v84, v85
	v_cvt_pk_bf16_f32 v86, v86, v87
	v_cvt_pk_bf16_f32 v87, v80, v81
	v_cvt_pk_bf16_f32 v83, v82, v83
	v_cndmask_b32_e64 v80, v92, v85, s[0:1]
	v_cndmask_b32_e64 v81, v93, v86, s[0:1]
	v_cndmask_b32_e64 v82, v88, v87, s[0:1]
	v_cndmask_b32_e64 v84, v89, v83, s[0:1]
	v_mov_b32_dpp v80, v80 row_ror:8 row_mask:0xf bank_mask:0xf bound_ctrl:1
	v_mov_b32_dpp v81, v81 row_ror:8 row_mask:0xf bank_mask:0xf bound_ctrl:1
	v_mov_b32_dpp v82, v82 row_ror:8 row_mask:0xf bank_mask:0xf bound_ctrl:1
	v_mov_b32_dpp v90, v84 row_ror:8 row_mask:0xf bank_mask:0xf bound_ctrl:1
	v_cndmask_b32_e64 v84, v80, v92, s[0:1]
	v_cndmask_b32_e64 v80, v85, v80, s[0:1]
	v_cndmask_b32_e64 v85, v81, v93, s[0:1]
	v_cndmask_b32_e64 v81, v86, v81, s[0:1]
	v_cndmask_b32_e64 v86, v82, v88, s[0:1]
	v_cndmask_b32_e64 v82, v87, v82, s[0:1]
	v_cndmask_b32_e64 v87, v90, v89, s[0:1]
	v_cndmask_b32_e64 v83, v83, v90, s[0:1]
	v_or_b32_e32 v90, 32, v142
	v_or_b32_e32 v88, 40, v142
	s_and_b64 vcc, exec, s[6:7]
	s_mov_b64 s[28:29], -1
	s_cbranch_vccnz .LBB0_210
	s_lshr_b32 vcc_lo, 0x1000, s17
	s_mov_b32 vcc_hi, 0
	v_lshl_add_u64 v[92:93], v[252:253], 0, vcc
	global_store_dwordx4 v[92:93], v[84:87], off
	v_lshl_add_u64 v[92:93], v[254:255], 0, vcc
	global_store_dwordx4 v[92:93], v[80:83], off
	s_cbranch_execz .LBB0_211

; __device__ __forceinline__ unsigned pk2(float lo, float hi) { f32x2_t v = {lo, hi}; bf16x2_t b = __builtin_convertvector(v, bf16x2_t); return __builtin_bit_cast(unsigned, b); }
; __device__ __forceinline__ float silu_f(float v) { return v * __builtin_amdgcn_rcpf(1.f + __builtin_amdgcn_exp2f(-v * LOG2E)); }
; template <int CTRL> __device__ __forceinline__ unsigned dpp_mov(unsigned v) { return (unsigned)__builtin_amdgcn_update_dpp(0, (int)v, CTRL, 0xF, 0xF, true); }
;     __device__ __forceinline__ void operator()(const pg8::f32x4 (&acc)[2][2][4][2], const pg8::Unit& u, int wr, int wc, int fr, int fq) const {
;     ...
;                 pg8::f32x4 a0 = acc[ai][0][m][0], a1 = acc[ai][0][m][1], b0 = acc[ai][1][m][0], b1 = acc[ai][1][m][1];
;                 if (act) {
; #pragma unroll
;                     for (int e = 0; e < 4; ++e) { a0[e] = silu_f(a0[e]); a1[e] = silu_f(a1[e]); b0[e] = silu_f(b0[e]); b1[e] = silu_f(b1[e]); } }
;                 u32x4 A, B; A.x = pk2(a0[0], a0[1]); A.y = pk2(a0[2], a0[3]); A.z = pk2(a1[0], a1[1]); A.w = pk2(a1[2], a1[3]);
;                 B.x = pk2(b0[0], b0[1]); B.y = pk2(b0[2], b0[3]); B.z = pk2(b1[0], b1[1]); B.w = pk2(b1[2], b1[3]);
;                 u32x4 snd, rcv;
; #pragma unroll
;                 for (int e = 0; e < 4; ++e) { snd[e] = hi8 ? A[e] : B[e]; rcv[e] = dpp_mov<0x128>(snd[e]); }
;                 u32x4 d1, d2;
; #pragma unroll
;                 for (int e = 0; e < 4; ++e) { d1[e] = hi8 ? rcv[e] : A[e]; d2[e] = hi8 ? B[e] : rcv[e]; }
;                 const int row1 = rbase + ai * 128 + m * 16, row2 = row1 + 8;
;                 if (qkv) {
;                     const int bb = row1 >> 13, t1 = row1 & (SEQ - 1), t2 = row2 & (SEQ - 1);
;                     const int p1 = (t1 & dmask) * Lc + (t1 >> dsh), p2 = (t2 & dmask) * Lc + (t2 >> dsh);
;                     bf16_t* hb = base + (size_t)bb * 24 * SEQ * 64 + ecol;
;                     *(u32x4*)(hb + (size_t)p1 * 64) = d1; *(u32x4*)(hb + (size_t)p2 * 64) = d2;
.Lp1_nn3:
	v_cvt_pk_bf16_f32 v76, v76, v77
	v_cvt_pk_bf16_f32 v77, v78, v79
	v_cvt_pk_bf16_f32 v72, v72, v73
	v_cvt_pk_bf16_f32 v73, v74, v75
	v_cvt_pk_bf16_f32 v69, v68, v69
	v_cvt_pk_bf16_f32 v70, v70, v71
	v_cvt_pk_bf16_f32 v71, v64, v65
	v_cvt_pk_bf16_f32 v67, v66, v67
	v_cndmask_b32_e64 v64, v76, v69, s[0:1]
	v_cndmask_b32_e64 v65, v77, v70, s[0:1]
	v_cndmask_b32_e64 v66, v72, v71, s[0:1]
	v_cndmask_b32_e64 v68, v73, v67, s[0:1]
	v_mov_b32_dpp v64, v64 row_ror:8 row_mask:0xf bank_mask:0xf bound_ctrl:1
	v_mov_b32_dpp v65, v65 row_ror:8 row_mask:0xf bank_mask:0xf bound_ctrl:1
	v_mov_b32_dpp v66, v66 row_ror:8 row_mask:0xf bank_mask:0xf bound_ctrl:1
	v_mov_b32_dpp v74, v68 row_ror:8 row_mask:0xf bank_mask:0xf bound_ctrl:1
	v_cndmask_b32_e64 v68, v64, v76, s[0:1]
	v_cndmask_b32_e64 v64, v69, v64, s[0:1]
	v_cndmask_b32_e64 v69, v65, v77, s[0:1]
	v_cndmask_b32_e64 v65, v70, v65, s[0:1]
	v_cndmask_b32_e64 v70, v66, v72, s[0:1]
	v_cndmask_b32_e64 v66, v71, v66, s[0:1]
	v_cndmask_b32_e64 v71, v74, v73, s[0:1]
	v_cndmask_b32_e64 v67, v67, v74, s[0:1]
	v_or_b32_e32 v74, 48, v142
	v_or_b32_e32 v72, 56, v142
	s_and_b64 vcc, exec, s[6:7]
	s_mov_b64 s[28:29], -1
	s_cbranch_vccnz .LBB0_212
	s_lshr_b32 vcc_lo, 0x1800, s17
	s_mov_b32 vcc_hi, 0
	v_lshl_add_u64 v[76:77], v[252:253], 0, vcc
	global_store_dwordx4 v[76:77], v[68:71], off
	v_lshl_add_u64 v[76:77], v[254:255], 0, vcc
	global_store_dwordx4 v[76:77], v[64:67], off
	s_cbranch_execz .LBB0_213

; __device__ __forceinline__ unsigned pk2(float lo, float hi) { f32x2_t v = {lo, hi}; bf16x2_t b = __builtin_convertvector(v, bf16x2_t); return __builtin_bit_cast(unsigned, b); }
; __device__ __forceinline__ float silu_f(float v) { return v * __builtin_amdgcn_rcpf(1.f + __builtin_amdgcn_exp2f(-v * LOG2E)); }
; template <int CTRL> __device__ __forceinline__ unsigned dpp_mov(unsigned v) { return (unsigned)__builtin_amdgcn_update_dpp(0, (int)v, CTRL, 0xF, 0xF, true); }
;     __device__ __forceinline__ void operator()(const pg8::f32x4 (&acc)[2][2][4][2], const pg8::Unit& u, int wr, int wc, int fr, int fq) const {
;     ...
;                 pg8::f32x4 a0 = acc[ai][0][m][0], a1 = acc[ai][0][m][1], b0 = acc[ai][1][m][0], b1 = acc[ai][1][m][1];
;                 if (act) {
; #pragma unroll
;                     for (int e = 0; e < 4; ++e) { a0[e] = silu_f(a0[e]); a1[e] = silu_f(a1[e]); b0[e] = silu_f(b0[e]); b1[e] = silu_f(b1[e]); } }
;                 u32x4 A, B; A.x = pk2(a0[0], a0[1]); A.y = pk2(a0[2], a0[3]); A.z = pk2(a1[0], a1[1]); A.w = pk2(a1[2], a1[3]);
;                 B.x = pk2(b0[0], b0[1]); B.y = pk2(b0[2], b0[3]); B.z = pk2(b1[0], b1[1]); B.w = pk2(b1[2], b1[3]);
;                 u32x4 snd, rcv;
; #pragma unroll
;                 for (int e = 0; e < 4; ++e) { snd[e] = hi8 ? A[e] : B[e]; rcv[e] = dpp_mov<0x128>(snd[e]); }
;                 u32x4 d1, d2;
; #pragma unroll
;                 for (int e = 0; e < 4; ++e) { d1[e] = hi8 ? rcv[e] : A[e]; d2[e] = hi8 ? B[e] : rcv[e]; }
;                 const int row1 = rbase + ai * 128 + m * 16, row2 = row1 + 8;
;                 if (qkv) {
;                     const int bb = row1 >> 13, t1 = row1 & (SEQ - 1), t2 = row2 & (SEQ - 1);
;                     const int p1 = (t1 & dmask) * Lc + (t1 >> dsh), p2 = (t2 & dmask) * Lc + (t2 >> dsh);
;                     bf16_t* hb = base + (size_t)bb * 24 * SEQ * 64 + ecol;
;                     *(u32x4*)(hb + (size_t)p1 * 64) = d1; *(u32x4*)(hb + (size_t)p2 * 64) = d2;
.Lp1_nn4:
	v_add_u32_e32 v66, 0x80, v142
	v_ashrrev_i32_e32 v64, 13, v66
	v_mul_i32_i24_e32 v64, 24, v64
	v_cvt_pk_bf16_f32 v60, v60, v61
	v_cvt_pk_bf16_f32 v61, v62, v63
	v_cvt_pk_bf16_f32 v56, v56, v57
	v_cvt_pk_bf16_f32 v57, v58, v59
	v_cvt_pk_bf16_f32 v53, v52, v53
	v_cvt_pk_bf16_f32 v54, v54, v55
	v_cvt_pk_bf16_f32 v55, v48, v49
	v_cvt_pk_bf16_f32 v51, v50, v51
	v_ashrrev_i32_e32 v65, 31, v64
	v_cndmask_b32_e64 v48, v60, v53, s[0:1]
	v_cndmask_b32_e64 v49, v61, v54, s[0:1]
	v_cndmask_b32_e64 v50, v56, v55, s[0:1]
	v_cndmask_b32_e64 v52, v57, v51, s[0:1]
	v_lshlrev_b64 v[64:65], 20, v[64:65]
	v_mov_b32_dpp v48, v48 row_ror:8 row_mask:0xf bank_mask:0xf bound_ctrl:1
	v_mov_b32_dpp v49, v49 row_ror:8 row_mask:0xf bank_mask:0xf bound_ctrl:1
	v_mov_b32_dpp v50, v50 row_ror:8 row_mask:0xf bank_mask:0xf bound_ctrl:1
	v_mov_b32_dpp v58, v52 row_ror:8 row_mask:0xf bank_mask:0xf bound_ctrl:1
	v_lshl_add_u64 v[64:65], v[140:141], 0, v[64:65]
	v_cndmask_b32_e64 v52, v48, v60, s[0:1]
	v_cndmask_b32_e64 v48, v53, v48, s[0:1]
	v_cndmask_b32_e64 v53, v49, v61, s[0:1]
	v_cndmask_b32_e64 v49, v54, v49, s[0:1]
	v_cndmask_b32_e64 v54, v50, v56, s[0:1]
	v_cndmask_b32_e64 v50, v55, v50, s[0:1]
	v_cndmask_b32_e64 v55, v58, v57, s[0:1]
	v_cndmask_b32_e64 v51, v51, v58, s[0:1]
	v_add_u32_e32 v56, 0x88, v142
	s_and_b64 vcc, exec, s[6:7]
	s_mov_b64 s[28:29], -1
	s_cbranch_vccnz .LBB0_214
	s_lshr_b32 vcc_lo, 0x4000, s17
	s_mov_b32 vcc_hi, 0
	v_lshl_add_u64 v[58:59], v[252:253], 0, vcc
	global_store_dwordx4 v[58:59], v[52:55], off
	v_lshl_add_u64 v[58:59], v[254:255], 0, vcc
	global_store_dwordx4 v[58:59], v[48:51], off
	s_cbranch_execz .LBB0_215

; __device__ __forceinline__ unsigned pk2(float lo, float hi) { f32x2_t v = {lo, hi}; bf16x2_t b = __builtin_convertvector(v, bf16x2_t); return __builtin_bit_cast(unsigned, b); }
; __device__ __forceinline__ float silu_f(float v) { return v * __builtin_amdgcn_rcpf(1.f + __builtin_amdgcn_exp2f(-v * LOG2E)); }
; template <int CTRL> __device__ __forceinline__ unsigned dpp_mov(unsigned v) { return (unsigned)__builtin_amdgcn_update_dpp(0, (int)v, CTRL, 0xF, 0xF, true); }
;     __device__ __forceinline__ void operator()(const pg8::f32x4 (&acc)[2][2][4][2], const pg8::Unit& u, int wr, int wc, int fr, int fq) const {
;     ...
;                 pg8::f32x4 a0 = acc[ai][0][m][0], a1 = acc[ai][0][m][1], b0 = acc[ai][1][m][0], b1 = acc[ai][1][m][1];
;                 if (act) {
; #pragma unroll
;                     for (int e = 0; e < 4; ++e) { a0[e] = silu_f(a0[e]); a1[e] = silu_f(a1[e]); b0[e] = silu_f(b0[e]); b1[e] = silu_f(b1[e]); } }
;                 u32x4 A, B; A.x = pk2(a0[0], a0[1]); A.y = pk2(a0[2], a0[3]); A.z = pk2(a1[0], a1[1]); A.w = pk2(a1[2], a1[3]);
;                 B.x = pk2(b0[0], b0[1]); B.y = pk2(b0[2], b0[3]); B.z = pk2(b1[0], b1[1]); B.w = pk2(b1[2], b1[3]);
;                 u32x4 snd, rcv;
; #pragma unroll
;                 for (int e = 0; e < 4; ++e) { snd[e] = hi8 ? A[e] : B[e]; rcv[e] = dpp_mov<0x128>(snd[e]); }
;                 u32x4 d1, d2;
; #pragma unroll
;                 for (int e = 0; e < 4; ++e) { d1[e] = hi8 ? rcv[e] : A[e]; d2[e] = hi8 ? B[e] : rcv[e]; }
;                 const int row1 = rbase + ai * 128 + m * 16, row2 = row1 + 8;
;                 if (qkv) {
;                     const int bb = row1 >> 13, t1 = row1 & (SEQ - 1), t2 = row2 & (SEQ - 1);
;                     const int p1 = (t1 & dmask) * Lc + (t1 >> dsh), p2 = (t2 & dmask) * Lc + (t2 >> dsh);
;                     bf16_t* hb = base + (size_t)bb * 24 * SEQ * 64 + ecol;
;                     *(u32x4*)(hb + (size_t)p1 * 64) = d1; *(u32x4*)(hb + (size_t)p2 * 64) = d2;
.Lp1_nn5:
	v_cvt_pk_bf16_f32 v44, v44, v45
	v_cvt_pk_bf16_f32 v45, v46, v47
	v_cvt_pk_bf16_f32 v40, v40, v41
	v_cvt_pk_bf16_f32 v41, v42, v43
	v_cvt_pk_bf16_f32 v37, v36, v37
	v_cvt_pk_bf16_f32 v38, v38, v39
	v_cvt_pk_bf16_f32 v39, v32, v33
	v_cvt_pk_bf16_f32 v35, v34, v35
	v_cndmask_b32_e64 v32, v44, v37, s[0:1]
	v_cndmask_b32_e64 v33, v45, v38, s[0:1]
	v_cndmask_b32_e64 v34, v40, v39, s[0:1]
	v_cndmask_b32_e64 v36, v41, v35, s[0:1]
	v_mov_b32_dpp v32, v32 row_ror:8 row_mask:0xf bank_mask:0xf bound_ctrl:1
	v_mov_b32_dpp v33, v33 row_ror:8 row_mask:0xf bank_mask:0xf bound_ctrl:1
	v_mov_b32_dpp v34, v34 row_ror:8 row_mask:0xf bank_mask:0xf bound_ctrl:1
	v_mov_b32_dpp v42, v36 row_ror:8 row_mask:0xf bank_mask:0xf bound_ctrl:1
	v_cndmask_b32_e64 v36, v32, v44, s[0:1]
	v_cndmask_b32_e64 v32, v37, v32, s[0:1]
	v_cndmask_b32_e64 v37, v33, v45, s[0:1]
	v_cndmask_b32_e64 v33, v38, v33, s[0:1]
	v_cndmask_b32_e64 v38, v34, v40, s[0:1]
	v_cndmask_b32_e64 v34, v39, v34, s[0:1]
	v_cndmask_b32_e64 v39, v42, v41, s[0:1]
	v_cndmask_b32_e64 v35, v35, v42, s[0:1]
	v_add_u32_e32 v42, 0x90, v142
	v_add_u32_e32 v40, 0x98, v142
	s_and_b64 vcc, exec, s[6:7]
	s_mov_b64 s[28:29], -1
	s_cbranch_vccnz .LBB0_216
	s_lshr_b32 vcc_lo, 0x4800, s17
	s_mov_b32 vcc_hi, 0
	v_lshl_add_u64 v[44:45], v[252:253], 0, vcc
	global_store_dwordx4 v[44:45], v[36:39], off
	v_lshl_add_u64 v[44:45], v[254:255], 0, vcc
	global_store_dwordx4 v[44:45], v[32:35], off
	s_cbranch_execz .LBB0_217

; __device__ __forceinline__ unsigned pk2(float lo, float hi) { f32x2_t v = {lo, hi}; bf16x2_t b = __builtin_convertvector(v, bf16x2_t); return __builtin_bit_cast(unsigned, b); }
; __device__ __forceinline__ float silu_f(float v) { return v * __builtin_amdgcn_rcpf(1.f + __builtin_amdgcn_exp2f(-v * LOG2E)); }
; template <int CTRL> __device__ __forceinline__ unsigned dpp_mov(unsigned v) { return (unsigned)__builtin_amdgcn_update_dpp(0, (int)v, CTRL, 0xF, 0xF, true); }
;     __device__ __forceinline__ void operator()(const pg8::f32x4 (&acc)[2][2][4][2], const pg8::Unit& u, int wr, int wc, int fr, int fq) const {
;     ...
;                 pg8::f32x4 a0 = acc[ai][0][m][0], a1 = acc[ai][0][m][1], b0 = acc[ai][1][m][0], b1 = acc[ai][1][m][1];
;                 if (act) {
; #pragma unroll
;                     for (int e = 0; e < 4; ++e) { a0[e] = silu_f(a0[e]); a1[e] = silu_f(a1[e]); b0[e] = silu_f(b0[e]); b1[e] = silu_f(b1[e]); } }
;                 u32x4 A, B; A.x = pk2(a0[0], a0[1]); A.y = pk2(a0[2], a0[3]); A.z = pk2(a1[0], a1[1]); A.w = pk2(a1[2], a1[3]);
;                 B.x = pk2(b0[0], b0[1]); B.y = pk2(b0[2], b0[3]); B.z = pk2(b1[0], b1[1]); B.w = pk2(b1[2], b1[3]);
;                 u32x4 snd, rcv;
; #pragma unroll
;                 for (int e = 0; e < 4; ++e) { snd[e] = hi8 ? A[e] : B[e]; rcv[e] = dpp_mov<0x128>(snd[e]); }
;                 u32x4 d1, d2;
; #pragma unroll
;                 for (int e = 0; e < 4; ++e) { d1[e] = hi8 ? rcv[e] : A[e]; d2[e] = hi8 ? B[e] : rcv[e]; }
;                 const int row1 = rbase + ai * 128 + m * 16, row2 = row1 + 8;
;                 if (qkv) {
;                     const int bb = row1 >> 13, t1 = row1 & (SEQ - 1), t2 = row2 & (SEQ - 1);
;                     const int p1 = (t1 & dmask) * Lc + (t1 >> dsh), p2 = (t2 & dmask) * Lc + (t2 >> dsh);
;                     bf16_t* hb = base + (size_t)bb * 24 * SEQ * 64 + ecol;
;                     *(u32x4*)(hb + (size_t)p1 * 64) = d1; *(u32x4*)(hb + (size_t)p2 * 64) = d2;
.Lp1_nn6:
	v_cvt_pk_bf16_f32 v28, v28, v29
	v_cvt_pk_bf16_f32 v29, v30, v31
	v_cvt_pk_bf16_f32 v24, v24, v25
	v_cvt_pk_bf16_f32 v25, v26, v27
	v_cvt_pk_bf16_f32 v21, v20, v21
	v_cvt_pk_bf16_f32 v22, v22, v23
	v_cvt_pk_bf16_f32 v23, v16, v17
	v_cvt_pk_bf16_f32 v19, v18, v19
	v_cndmask_b32_e64 v16, v28, v21, s[0:1]
	v_cndmask_b32_e64 v17, v29, v22, s[0:1]
	v_cndmask_b32_e64 v18, v24, v23, s[0:1]
	v_cndmask_b32_e64 v20, v25, v19, s[0:1]
	v_mov_b32_dpp v16, v16 row_ror:8 row_mask:0xf bank_mask:0xf bound_ctrl:1
	v_mov_b32_dpp v17, v17 row_ror:8 row_mask:0xf bank_mask:0xf bound_ctrl:1
	v_mov_b32_dpp v18, v18 row_ror:8 row_mask:0xf bank_mask:0xf bound_ctrl:1
	v_mov_b32_dpp v26, v20 row_ror:8 row_mask:0xf bank_mask:0xf bound_ctrl:1
	v_cndmask_b32_e64 v20, v16, v28, s[0:1]
	v_cndmask_b32_e64 v16, v21, v16, s[0:1]
	v_cndmask_b32_e64 v21, v17, v29, s[0:1]
	v_cndmask_b32_e64 v17, v22, v17, s[0:1]
	v_cndmask_b32_e64 v22, v18, v24, s[0:1]
	v_cndmask_b32_e64 v18, v23, v18, s[0:1]
	v_cndmask_b32_e64 v23, v26, v25, s[0:1]
	v_cndmask_b32_e64 v19, v19, v26, s[0:1]
	v_add_u32_e32 v26, 0xa0, v142
	v_add_u32_e32 v24, 0xa8, v142
	s_and_b64 vcc, exec, s[6:7]
	s_mov_b64 s[28:29], -1
	s_cbranch_vccnz .LBB0_218
	s_lshr_b32 vcc_lo, 0x5000, s17
	s_mov_b32 vcc_hi, 0
	v_lshl_add_u64 v[28:29], v[252:253], 0, vcc
	global_store_dwordx4 v[28:29], v[20:23], off
	v_lshl_add_u64 v[28:29], v[254:255], 0, vcc
	global_store_dwordx4 v[28:29], v[16:19], off
	s_cbranch_execz .LBB0_219

; __device__ __forceinline__ unsigned pk2(float lo, float hi) { f32x2_t v = {lo, hi}; bf16x2_t b = __builtin_convertvector(v, bf16x2_t); return __builtin_bit_cast(unsigned, b); }
; __device__ __forceinline__ float silu_f(float v) { return v * __builtin_amdgcn_rcpf(1.f + __builtin_amdgcn_exp2f(-v * LOG2E)); }
; template <int CTRL> __device__ __forceinline__ unsigned dpp_mov(unsigned v) { return (unsigned)__builtin_amdgcn_update_dpp(0, (int)v, CTRL, 0xF, 0xF, true); }
;     __device__ __forceinline__ void operator()(const pg8::f32x4 (&acc)[2][2][4][2], const pg8::Unit& u, int wr, int wc, int fr, int fq) const {
;     ...
;                 pg8::f32x4 a0 = acc[ai][0][m][0], a1 = acc[ai][0][m][1], b0 = acc[ai][1][m][0], b1 = acc[ai][1][m][1];
;                 if (act) {
; #pragma unroll
;                     for (int e = 0; e < 4; ++e) { a0[e] = silu_f(a0[e]); a1[e] = silu_f(a1[e]); b0[e] = silu_f(b0[e]); b1[e] = silu_f(b1[e]); } }
;                 u32x4 A, B; A.x = pk2(a0[0], a0[1]); A.y = pk2(a0[2], a0[3]); A.z = pk2(a1[0], a1[1]); A.w = pk2(a1[2], a1[3]);
;                 B.x = pk2(b0[0], b0[1]); B.y = pk2(b0[2], b0[3]); B.z = pk2(b1[0], b1[1]); B.w = pk2(b1[2], b1[3]);
;                 u32x4 snd, rcv;
; #pragma unroll
;                 for (int e = 0; e < 4; ++e) { snd[e] = hi8 ? A[e] : B[e]; rcv[e] = dpp_mov<0x128>(snd[e]); }
;                 u32x4 d1, d2;
; #pragma unroll
;                 for (int e = 0; e < 4; ++e) { d1[e] = hi8 ? rcv[e] : A[e]; d2[e] = hi8 ? B[e] : rcv[e]; }
;                 const int row1 = rbase + ai * 128 + m * 16, row2 = row1 + 8;
;                 if (qkv) {
;                     const int bb = row1 >> 13, t1 = row1 & (SEQ - 1), t2 = row2 & (SEQ - 1);
;                     const int p1 = (t1 & dmask) * Lc + (t1 >> dsh), p2 = (t2 & dmask) * Lc + (t2 >> dsh);
;                     bf16_t* hb = base + (size_t)bb * 24 * SEQ * 64 + ecol;
;                     *(u32x4*)(hb + (size_t)p1 * 64) = d1; *(u32x4*)(hb + (size_t)p2 * 64) = d2;
.Lp1_nn7:
	v_cvt_pk_bf16_f32 v12, v12, v13
	v_cvt_pk_bf16_f32 v13, v14, v15
	v_cvt_pk_bf16_f32 v8, v8, v9
	v_cvt_pk_bf16_f32 v9, v10, v11
	v_cvt_pk_bf16_f32 v5, v4, v5
	v_cvt_pk_bf16_f32 v6, v6, v7
	v_cvt_pk_bf16_f32 v7, v0, v1
	v_cvt_pk_bf16_f32 v3, v2, v3
	v_cndmask_b32_e64 v0, v12, v5, s[0:1]
	v_cndmask_b32_e64 v1, v13, v6, s[0:1]
	v_cndmask_b32_e64 v2, v8, v7, s[0:1]
	v_cndmask_b32_e64 v4, v9, v3, s[0:1]
	v_mov_b32_dpp v0, v0 row_ror:8 row_mask:0xf bank_mask:0xf bound_ctrl:1
	v_mov_b32_dpp v1, v1 row_ror:8 row_mask:0xf bank_mask:0xf bound_ctrl:1
	v_mov_b32_dpp v2, v2 row_ror:8 row_mask:0xf bank_mask:0xf bound_ctrl:1
	v_mov_b32_dpp v10, v4 row_ror:8 row_mask:0xf bank_mask:0xf bound_ctrl:1
	v_cndmask_b32_e64 v4, v0, v12, s[0:1]
	v_cndmask_b32_e64 v0, v5, v0, s[0:1]
	v_cndmask_b32_e64 v5, v1, v13, s[0:1]
	v_cndmask_b32_e64 v1, v6, v1, s[0:1]
	v_cndmask_b32_e64 v6, v2, v8, s[0:1]
	v_cndmask_b32_e64 v2, v7, v2, s[0:1]
	v_cndmask_b32_e64 v7, v10, v9, s[0:1]
	v_cndmask_b32_e64 v3, v3, v10, s[0:1]
	v_add_u32_e32 v10, 0xb0, v142
	v_add_u32_e32 v8, 0xb8, v142
	s_and_b64 vcc, exec, s[6:7]
	s_mov_b64 s[4:5], -1
	s_cbranch_vccnz .LBB0_220
	s_lshr_b32 vcc_lo, 0x5800, s17
	s_mov_b32 vcc_hi, 0
	v_lshl_add_u64 v[12:13], v[252:253], 0, vcc
	global_store_dwordx4 v[12:13], v[4:7], off
	v_lshl_add_u64 v[12:13], v[254:255], 0, vcc
	global_store_dwordx4 v[12:13], v[0:3], off
	s_cbranch_execz .LBB0_221
